# seam mask: all seams after phases 2..27 XCD-local again (no global resync at layer boundaries), on top of the combine-DPP version
# baseline (speedup 1.0000x reference)
; #define LAS __attribute__((address_space(3)))
; __device__ __forceinline__ unsigned xb_ld(unsigned* p)              { return __hip_atomic_load(p, __ATOMIC_RELAXED, __HIP_MEMORY_SCOPE_AGENT); }
; __device__ __forceinline__ unsigned xb_add(unsigned* p, unsigned v) { return __hip_atomic_fetch_add(p, v, __ATOMIC_RELAXED, __HIP_MEMORY_SCOPE_AGENT); }
; __device__ __forceinline__ unsigned xb_xcc_id() { return (unsigned)__builtin_amdgcn_s_getreg((3 << 11) | 20) & 0xFu; }
; #define XB_SPIN(cond, bar) do { unsigned _sp = 0; while (cond) { __builtin_amdgcn_s_sleep(1); \
;     if ((++_sp & 255u) == 0u) { if (xb_ld(&(bar)[XB_TMO])) break; if (_sp > XB_SPIN_CAP) { atomicAdd(&(bar)[XB_TMO], 1u); break; } } } } while (0)
; __device__ __forceinline__ void xcd_barrier(const XcdBarrier& b) {
;     asm volatile("s_waitcnt vmcnt(0)" ::: "memory");
;     __syncthreads();
;     if (threadIdx.x == 0) {
;         unsigned* bar = b.bar;
;         __builtin_amdgcn_s_waitcnt(0);
;         unsigned nloc = b.st[0], nx = b.st[1];
;         if (nloc == 0u) { xcd_barrier_complete(bar, b.x, nloc, nx); b.st[0] = nloc; b.st[1] = nx; }
;         const unsigned old = xb_add(&bar[XB_XSUB(b.x)], 1u);
;         const unsigned gen = old / nloc;
;         if (old + 1u == (gen + 1u) * nloc) {
;             __builtin_amdgcn_fence(__ATOMIC_RELEASE, "agent");
;             asm volatile("s_waitcnt vmcnt(0)" ::: "memory");
;             const unsigned og = xb_add(&bar[XB_TOP], 1u);
;             const unsigned tg = og / nx;
;             if (og + 1u == (tg + 1u) * nx) xb_add(&bar[XB_TOPGEN], 1u);
;             else XB_SPIN(xb_ld(&bar[XB_TOPGEN]) == tg, bar);
;             __builtin_amdgcn_fence(__ATOMIC_ACQUIRE, "agent");
;             xb_add(&bar[XB_XGEN(b.x)], 1u);
;             asm volatile("s_waitcnt vmcnt(0)" ::: "memory");
;         } else {
;             XB_SPIN(xb_ld(&bar[XB_XGEN(b.x)]) == gen, bar);
;             __builtin_amdgcn_fence(__ATOMIC_ACQUIRE, "agent");
;             asm volatile("s_waitcnt vmcnt(0)" ::: "memory");
;         }
;     }
;     __syncthreads();
; }
; __global__ void __launch_bounds__(NWAVES * 64, 2) trunk_fwd(Args args) {
;     ...
;         if (ph + 1 < ph_hi) { XcdBarrier xb_; xb_.bar = (unsigned*)ws; xb_.x = xb_xcc_id(); xb_.st = (volatile LAS unsigned*)(L + XB_ST_OFF); xcd_barrier(xb_); }
.LBB0_652:
	s_andn2_saveexec_b64 s[8:9], s[8:9]
	s_cbranch_execz .LBB0_169
	s_mov_b64 s[8:9], exec
	s_waitcnt lgkmcnt(0)
	v_readlane_b32 s0, v255, 9
	s_lshl_b32 s0, 1, s0
	s_and_b32 s0, s0, 0x1ffffff8
	s_cbranch_scc0 .Lxb_global
	v_readlane_b32 s0, v255, 42
	s_cmp_eq_u32 s0, 0
	s_cbranch_scc1 .Lxb_local
